# gate3 loop: issue all 8 LDS-DMA pieces right after the tail group
# speedup vs baseline: 1.0016x; 1.0016x over previous
; __device__ __forceinline__ void gemm_gate3(f32x4 (&g)[3][2][4], const bf16_t* __restrict__ A, const bf16_t* __restrict__ Bt0, int nk, unsigned char* lds, int tid) {
;     ...
;     for (int kt = 0; kt < nk; ++kt) {
;         if (!late && kt + 1 < nk) issue(kt + 1, (kt + 1) & 1);
;         const unsigned char* As = lds + (kt & 1) * STAGE;
;         const unsigned char* Bs = As + 128 * 128;
; #pragma unroll
;         for (int ks = 0; ks < 2; ++ks) {
;             if (ks == 1 && late && kt + 1 < nk) issue(kt + 1, (kt + 1) & 1);
;             const int co = ((ks * 4 + fq) ^ sz) * 16;
;             bf16x8 af[2];
; #pragma unroll
;             for (int m = 0; m < 2; ++m) af[m] = *(const bf16x8*)(As + (wr * 32 + m * 16 + fr) * 128 + co);
; #pragma unroll
;             for (int i = 0; i < 3; ++i) {
;                 bf16x8 bfr[4];
; #pragma unroll
;                 for (int n = 0; n < 4; ++n) bfr[n] = *(const bf16x8*)(Bs + (i * 128 + wc * 64 + n * 16 + fr) * 128 + co);
; #pragma unroll
;                 for (int m = 0; m < 2; ++m)
; #pragma unroll
;                     for (int n = 0; n < 4; ++n) g[i][m][n] = __builtin_amdgcn_mfma_f32_16x16x32_bf16(bfr[n], af[m], g[i][m][n], 0, 0, 0);
;                 if (i < 2) __builtin_amdgcn_sched_barrier(0);
;             }
;         }
;         asm volatile("s_waitcnt vmcnt(0) lgkmcnt(0)" ::: "memory");
;         __builtin_amdgcn_s_barrier();
;         asm volatile("" ::: "memory");
;     }
.LBB0_687:
	s_mov_b32 s75, 0
	v_readlane_b32 s76, v253, 0
	s_lshr_b32 s50, s76, 3
	s_and_b32 s50, s50, 15
	s_lshl_b32 s50, s50, 7
	s_cmpk_eq_i32 s50, 0x780
	s_cselect_b32 s50, 0, s50
	s_mov_b32 s51, 0
	s_mov_b32 s47, 0
	s_lshl_b32 s54, s75, 16
	s_xor_b32 s70, s54, 0x10000
	s_add_i32 s70, s7, s70
	v_add3_u32 v155, s54, v129, v103
	v_add3_u32 v154, s54, v129, v101
	v_add3_u32 v157, s54, v130, v103
	v_add3_u32 v156, s54, v130, v101
	ds_read_b128 v[190:193], v154
	ds_read_b128 v[194:197], v154 offset:2048
	ds_read_b128 v[138:141], v155 offset:16384
	ds_read_b128 v[142:145], v155 offset:18432
	ds_read_b128 v[146:149], v155 offset:20480
	ds_read_b128 v[150:153], v155 offset:22528
	ds_read_b128 v[214:217], v155 offset:32768
	ds_read_b128 v[218:221], v155 offset:34816
	ds_read_b128 v[222:225], v155 offset:36864
	ds_read_b128 v[226:229], v155 offset:38912
	v_lshl_add_u64 v[246:247], v[122:123], 0, s[50:51]
	v_lshl_add_u64 v[248:249], v[120:121], 0, s[50:51]
	v_lshl_add_u64 v[250:251], v[246:247], 0, s[94:95]
	s_mov_b32 m0, s70
	s_nop 0
	global_load_lds_dwordx4 v[250:251], off
	v_lshl_add_u64 v[206:207], v[246:247], 0, s[14:15]
	s_add_i32 m0, s70, 0x2000
	s_nop 0
	global_load_lds_dwordx4 v[206:207], off
	v_lshl_add_u64 v[250:251], v[248:249], 0, s[16:17]
	s_add_i32 m0, s70, 0x4000
	s_nop 0
	global_load_lds_dwordx4 v[250:251], off
	v_lshl_add_u64 v[206:207], v[248:249], 0, s[24:25]
	s_add_i32 m0, s70, 0x6000
	s_nop 0
	global_load_lds_dwordx4 v[206:207], off
	s_mov_b64 s[56:57], 0x202080
	v_lshl_add_u64 v[250:251], v[248:249], 0, s[56:57]
	s_add_i32 m0, s70, 0x8000
	s_nop 0
	global_load_lds_dwordx4 v[250:251], off
	s_mov_b64 s[56:57], 0x222080
	v_lshl_add_u64 v[206:207], v[248:249], 0, s[56:57]
	s_add_i32 m0, s70, 0xa000
	s_nop 0
	global_load_lds_dwordx4 v[206:207], off
	s_mov_b64 s[56:57], 0x402080
	v_lshl_add_u64 v[250:251], v[248:249], 0, s[56:57]
	s_add_i32 m0, s70, 0xc000
	s_nop 0
	global_load_lds_dwordx4 v[250:251], off
	s_mov_b64 s[56:57], 0x422080
	v_lshl_add_u64 v[206:207], v[248:249], 0, s[56:57]
	s_add_i32 m0, s70, 0xe000
	s_nop 0
	global_load_lds_dwordx4 v[206:207], off
	ds_read_b128 v[230:233], v155 offset:49152
	ds_read_b128 v[234:237], v155 offset:51200
	ds_read_b128 v[238:241], v155 offset:53248
	s_waitcnt lgkmcnt(12)
	ds_read_b128 v[242:245], v155 offset:55296
	s_waitcnt lgkmcnt(12)
	ds_read_b128 v[198:201], v156
	s_waitcnt lgkmcnt(12)
	ds_read_b128 v[202:205], v156 offset:2048
	s_waitcnt lgkmcnt(10)
	v_mfma_f32_16x16x32_bf16 v[92:95], v[138:141], v[190:193], v[92:95]
	v_mfma_f32_16x16x32_bf16 v[88:91], v[142:145], v[190:193], v[88:91]
	v_mfma_f32_16x16x32_bf16 v[84:87], v[146:149], v[190:193], v[84:87]
	v_mfma_f32_16x16x32_bf16 v[80:83], v[150:153], v[190:193], v[80:83]
	v_mfma_f32_16x16x32_bf16 v[76:79], v[138:141], v[194:197], v[76:79]
	v_mfma_f32_16x16x32_bf16 v[72:75], v[142:145], v[194:197], v[72:75]
	v_mfma_f32_16x16x32_bf16 v[68:71], v[146:149], v[194:197], v[68:71]
	v_mfma_f32_16x16x32_bf16 v[64:67], v[150:153], v[194:197], v[64:67]
	ds_read_b128 v[138:141], v157 offset:16384
	ds_read_b128 v[142:145], v157 offset:18432
	ds_read_b128 v[146:149], v157 offset:20480
	s_waitcnt lgkmcnt(12)
	ds_read_b128 v[150:153], v157 offset:22528
	s_waitcnt lgkmcnt(10)
	v_mfma_f32_16x16x32_bf16 v[60:63], v[214:217], v[190:193], v[60:63]
	v_mfma_f32_16x16x32_bf16 v[52:55], v[218:221], v[190:193], v[52:55]
	v_mfma_f32_16x16x32_bf16 v[48:51], v[222:225], v[190:193], v[48:51]
	v_mfma_f32_16x16x32_bf16 v[44:47], v[226:229], v[190:193], v[44:47]
	v_mfma_f32_16x16x32_bf16 v[40:43], v[214:217], v[194:197], v[40:43]
	v_mfma_f32_16x16x32_bf16 v[36:39], v[218:221], v[194:197], v[36:39]
	v_mfma_f32_16x16x32_bf16 v[32:35], v[222:225], v[194:197], v[32:35]
	v_mfma_f32_16x16x32_bf16 v[28:31], v[226:229], v[194:197], v[28:31]
	ds_read_b128 v[214:217], v157 offset:32768
	ds_read_b128 v[218:221], v157 offset:34816
	ds_read_b128 v[222:225], v157 offset:36864
	s_waitcnt lgkmcnt(12)
	ds_read_b128 v[226:229], v157 offset:38912
	s_waitcnt lgkmcnt(10)
	v_mfma_f32_16x16x32_bf16 v[24:27], v[230:233], v[190:193], v[24:27]
	v_mfma_f32_16x16x32_bf16 v[20:23], v[234:237], v[190:193], v[20:23]
	v_mfma_f32_16x16x32_bf16 v[16:19], v[238:241], v[190:193], v[16:19]
	v_mfma_f32_16x16x32_bf16 v[12:15], v[242:245], v[190:193], v[12:15]
	v_mfma_f32_16x16x32_bf16 v[8:11], v[230:233], v[194:197], v[8:11]
	v_mfma_f32_16x16x32_bf16 v[4:7], v[234:237], v[194:197], v[4:7]
	v_mfma_f32_16x16x32_bf16 v[0:3], v[238:241], v[194:197], v[0:3]
	v_mfma_f32_16x16x32_bf16 v[56:59], v[242:245], v[194:197], v[56:59]
	ds_read_b128 v[230:233], v157 offset:49152
	ds_read_b128 v[234:237], v157 offset:51200
	ds_read_b128 v[238:241], v157 offset:53248
	s_waitcnt lgkmcnt(12)
	ds_read_b128 v[242:245], v157 offset:55296
	s_waitcnt lgkmcnt(8)
	v_mfma_f32_16x16x32_bf16 v[92:95], v[138:141], v[198:201], v[92:95]
	v_mfma_f32_16x16x32_bf16 v[88:91], v[142:145], v[198:201], v[88:91]
	v_mfma_f32_16x16x32_bf16 v[84:87], v[146:149], v[198:201], v[84:87]
	v_mfma_f32_16x16x32_bf16 v[80:83], v[150:153], v[198:201], v[80:83]
	v_mfma_f32_16x16x32_bf16 v[76:79], v[138:141], v[202:205], v[76:79]
	v_mfma_f32_16x16x32_bf16 v[72:75], v[142:145], v[202:205], v[72:75]
	v_mfma_f32_16x16x32_bf16 v[68:71], v[146:149], v[202:205], v[68:71]
	v_mfma_f32_16x16x32_bf16 v[64:67], v[150:153], v[202:205], v[64:67]
	s_waitcnt lgkmcnt(4)
	v_mfma_f32_16x16x32_bf16 v[60:63], v[214:217], v[198:201], v[60:63]
	v_mfma_f32_16x16x32_bf16 v[52:55], v[218:221], v[198:201], v[52:55]
	v_mfma_f32_16x16x32_bf16 v[48:51], v[222:225], v[198:201], v[48:51]
	v_mfma_f32_16x16x32_bf16 v[44:47], v[226:229], v[198:201], v[44:47]
	v_mfma_f32_16x16x32_bf16 v[40:43], v[214:217], v[202:205], v[40:43]
	v_mfma_f32_16x16x32_bf16 v[36:39], v[218:221], v[202:205], v[36:39]
	v_mfma_f32_16x16x32_bf16 v[32:35], v[222:225], v[202:205], v[32:35]
	v_mfma_f32_16x16x32_bf16 v[28:31], v[226:229], v[202:205], v[28:31]
	s_add_u32 s50, s50, 0x80
	s_cmpk_eq_i32 s50, 0x780
	s_cselect_b32 s50, 0, s50
	s_add_i32 s47, s47, 1
	s_xor_b32 s75, s75, 1
	s_waitcnt vmcnt(0) lgkmcnt(0)
	s_barrier
; __device__ __forceinline__ void gemm_gate3(f32x4 (&g)[3][2][4], const bf16_t* __restrict__ A, const bf16_t* __restrict__ Bt0, int nk, unsigned char* lds, int tid) {
;     ...
;     for (int kt = 0; kt < nk; ++kt) {
;         if (!late && kt + 1 < nk) issue(kt + 1, (kt + 1) & 1);
;         const unsigned char* As = lds + (kt & 1) * STAGE;
;         const unsigned char* Bs = As + 128 * 128;
; #pragma unroll
;         for (int ks = 0; ks < 2; ++ks) {
;             if (ks == 1 && late && kt + 1 < nk) issue(kt + 1, (kt + 1) & 1);
;             const int co = ((ks * 4 + fq) ^ sz) * 16;
;             bf16x8 af[2];
; #pragma unroll
;             for (int m = 0; m < 2; ++m) af[m] = *(const bf16x8*)(As + (wr * 32 + m * 16 + fr) * 128 + co);
; #pragma unroll
;             for (int i = 0; i < 3; ++i) {
;                 bf16x8 bfr[4];
; #pragma unroll
;                 for (int n = 0; n < 4; ++n) bfr[n] = *(const bf16x8*)(Bs + (i * 128 + wc * 64 + n * 16 + fr) * 128 + co);
; #pragma unroll
;                 for (int m = 0; m < 2; ++m)
; #pragma unroll
;                     for (int n = 0; n < 4; ++n) g[i][m][n] = __builtin_amdgcn_mfma_f32_16x16x32_bf16(bfr[n], af[m], g[i][m][n], 0, 0, 0);
;                 if (i < 2) __builtin_amdgcn_sched_barrier(0);
;             }
;         }
;         asm volatile("s_waitcnt vmcnt(0) lgkmcnt(0)" ::: "memory");
;         __builtin_amdgcn_s_barrier();
;         asm volatile("" ::: "memory");
;     }
.Lp4_gloop:
	s_lshl_b32 s54, s75, 16
	s_xor_b32 s70, s54, 0x10000
	s_add_i32 s70, s7, s70
	v_add3_u32 v155, s54, v129, v103
	v_add3_u32 v154, s54, v129, v101
	v_add3_u32 v157, s54, v130, v103
	v_add3_u32 v156, s54, v130, v101
	ds_read_b128 v[190:193], v154
	ds_read_b128 v[194:197], v154 offset:2048
	ds_read_b128 v[138:141], v155 offset:16384
	ds_read_b128 v[142:145], v155 offset:18432
	ds_read_b128 v[146:149], v155 offset:20480
	ds_read_b128 v[150:153], v155 offset:22528
	ds_read_b128 v[214:217], v155 offset:32768
	ds_read_b128 v[218:221], v155 offset:34816
	ds_read_b128 v[222:225], v155 offset:36864
	ds_read_b128 v[226:229], v155 offset:38912
	v_lshl_add_u64 v[246:247], v[122:123], 0, s[50:51]
	v_lshl_add_u64 v[248:249], v[120:121], 0, s[50:51]
	v_mfma_f32_16x16x32_bf16 v[24:27], v[230:233], v[198:201], v[24:27]
	v_mfma_f32_16x16x32_bf16 v[20:23], v[234:237], v[198:201], v[20:23]
	v_mfma_f32_16x16x32_bf16 v[16:19], v[238:241], v[198:201], v[16:19]
	v_mfma_f32_16x16x32_bf16 v[12:15], v[242:245], v[198:201], v[12:15]
	v_mfma_f32_16x16x32_bf16 v[8:11], v[230:233], v[202:205], v[8:11]
	v_mfma_f32_16x16x32_bf16 v[4:7], v[234:237], v[202:205], v[4:7]
	v_mfma_f32_16x16x32_bf16 v[0:3], v[238:241], v[202:205], v[0:3]
	v_mfma_f32_16x16x32_bf16 v[56:59], v[242:245], v[202:205], v[56:59]
	v_lshl_add_u64 v[250:251], v[246:247], 0, s[94:95]
	s_mov_b32 m0, s70
	s_nop 0
	global_load_lds_dwordx4 v[250:251], off
	v_lshl_add_u64 v[206:207], v[246:247], 0, s[14:15]
	s_add_i32 m0, s70, 0x2000
	s_nop 0
	global_load_lds_dwordx4 v[206:207], off
	v_lshl_add_u64 v[250:251], v[248:249], 0, s[16:17]
	s_add_i32 m0, s70, 0x4000
	s_nop 0
	global_load_lds_dwordx4 v[250:251], off
	v_lshl_add_u64 v[206:207], v[248:249], 0, s[24:25]
	s_add_i32 m0, s70, 0x6000
	s_nop 0
	global_load_lds_dwordx4 v[206:207], off
	s_mov_b64 s[56:57], 0x202080
	v_lshl_add_u64 v[250:251], v[248:249], 0, s[56:57]
	s_add_i32 m0, s70, 0x8000
	s_nop 0
	global_load_lds_dwordx4 v[250:251], off
	s_mov_b64 s[56:57], 0x222080
	v_lshl_add_u64 v[206:207], v[248:249], 0, s[56:57]
	s_add_i32 m0, s70, 0xa000
	s_nop 0
	global_load_lds_dwordx4 v[206:207], off
	s_mov_b64 s[56:57], 0x402080
	v_lshl_add_u64 v[250:251], v[248:249], 0, s[56:57]
	s_add_i32 m0, s70, 0xc000
	s_nop 0
	global_load_lds_dwordx4 v[250:251], off
	s_mov_b64 s[56:57], 0x422080
	v_lshl_add_u64 v[206:207], v[248:249], 0, s[56:57]
	s_add_i32 m0, s70, 0xe000
	s_nop 0
	global_load_lds_dwordx4 v[206:207], off
	s_waitcnt lgkmcnt(0)
	ds_read_b128 v[230:233], v155 offset:49152
	ds_read_b128 v[234:237], v155 offset:51200
	ds_read_b128 v[238:241], v155 offset:53248
	ds_read_b128 v[242:245], v155 offset:55296
	ds_read_b128 v[198:201], v156
	ds_read_b128 v[202:205], v156 offset:2048
	v_mfma_f32_16x16x32_bf16 v[92:95], v[138:141], v[190:193], v[92:95]
	v_mfma_f32_16x16x32_bf16 v[88:91], v[142:145], v[190:193], v[88:91]
	v_mfma_f32_16x16x32_bf16 v[84:87], v[146:149], v[190:193], v[84:87]
	v_mfma_f32_16x16x32_bf16 v[80:83], v[150:153], v[190:193], v[80:83]
	v_mfma_f32_16x16x32_bf16 v[76:79], v[138:141], v[194:197], v[76:79]
	v_mfma_f32_16x16x32_bf16 v[72:75], v[142:145], v[194:197], v[72:75]
	v_mfma_f32_16x16x32_bf16 v[68:71], v[146:149], v[194:197], v[68:71]
	v_mfma_f32_16x16x32_bf16 v[64:67], v[150:153], v[194:197], v[64:67]
	ds_read_b128 v[138:141], v157 offset:16384
	ds_read_b128 v[142:145], v157 offset:18432
	ds_read_b128 v[146:149], v157 offset:20480
	ds_read_b128 v[150:153], v157 offset:22528
	v_mfma_f32_16x16x32_bf16 v[60:63], v[214:217], v[190:193], v[60:63]
	v_mfma_f32_16x16x32_bf16 v[52:55], v[218:221], v[190:193], v[52:55]
	v_mfma_f32_16x16x32_bf16 v[48:51], v[222:225], v[190:193], v[48:51]
	v_mfma_f32_16x16x32_bf16 v[44:47], v[226:229], v[190:193], v[44:47]
	v_mfma_f32_16x16x32_bf16 v[40:43], v[214:217], v[194:197], v[40:43]
	v_mfma_f32_16x16x32_bf16 v[36:39], v[218:221], v[194:197], v[36:39]
	v_mfma_f32_16x16x32_bf16 v[32:35], v[222:225], v[194:197], v[32:35]
	v_mfma_f32_16x16x32_bf16 v[28:31], v[226:229], v[194:197], v[28:31]
	ds_read_b128 v[214:217], v157 offset:32768
	ds_read_b128 v[218:221], v157 offset:34816
	ds_read_b128 v[222:225], v157 offset:36864
	s_waitcnt lgkmcnt(12)
	ds_read_b128 v[226:229], v157 offset:38912
	s_waitcnt lgkmcnt(10)
	v_mfma_f32_16x16x32_bf16 v[24:27], v[230:233], v[190:193], v[24:27]
	v_mfma_f32_16x16x32_bf16 v[20:23], v[234:237], v[190:193], v[20:23]
	v_mfma_f32_16x16x32_bf16 v[16:19], v[238:241], v[190:193], v[16:19]
	v_mfma_f32_16x16x32_bf16 v[12:15], v[242:245], v[190:193], v[12:15]
	v_mfma_f32_16x16x32_bf16 v[8:11], v[230:233], v[194:197], v[8:11]
	v_mfma_f32_16x16x32_bf16 v[4:7], v[234:237], v[194:197], v[4:7]
	v_mfma_f32_16x16x32_bf16 v[0:3], v[238:241], v[194:197], v[0:3]
	v_mfma_f32_16x16x32_bf16 v[56:59], v[242:245], v[194:197], v[56:59]
	ds_read_b128 v[230:233], v157 offset:49152
	ds_read_b128 v[234:237], v157 offset:51200
	ds_read_b128 v[238:241], v157 offset:53248
	s_waitcnt lgkmcnt(12)
	ds_read_b128 v[242:245], v157 offset:55296
	s_waitcnt lgkmcnt(8)
	v_mfma_f32_16x16x32_bf16 v[92:95], v[138:141], v[198:201], v[92:95]
	v_mfma_f32_16x16x32_bf16 v[88:91], v[142:145], v[198:201], v[88:91]
	v_mfma_f32_16x16x32_bf16 v[84:87], v[146:149], v[198:201], v[84:87]
	v_mfma_f32_16x16x32_bf16 v[80:83], v[150:153], v[198:201], v[80:83]
	v_mfma_f32_16x16x32_bf16 v[76:79], v[138:141], v[202:205], v[76:79]
	v_mfma_f32_16x16x32_bf16 v[72:75], v[142:145], v[202:205], v[72:75]
	v_mfma_f32_16x16x32_bf16 v[68:71], v[146:149], v[202:205], v[68:71]
	v_mfma_f32_16x16x32_bf16 v[64:67], v[150:153], v[202:205], v[64:67]
	s_waitcnt lgkmcnt(4)
	v_mfma_f32_16x16x32_bf16 v[60:63], v[214:217], v[198:201], v[60:63]
	v_mfma_f32_16x16x32_bf16 v[52:55], v[218:221], v[198:201], v[52:55]
	v_mfma_f32_16x16x32_bf16 v[48:51], v[222:225], v[198:201], v[48:51]
	v_mfma_f32_16x16x32_bf16 v[44:47], v[226:229], v[198:201], v[44:47]
	v_mfma_f32_16x16x32_bf16 v[40:43], v[214:217], v[202:205], v[40:43]
	v_mfma_f32_16x16x32_bf16 v[36:39], v[218:221], v[202:205], v[36:39]
	v_mfma_f32_16x16x32_bf16 v[32:35], v[222:225], v[202:205], v[32:35]
	v_mfma_f32_16x16x32_bf16 v[28:31], v[226:229], v[202:205], v[28:31]
	s_add_u32 s50, s50, 0x80
	s_cmpk_eq_i32 s50, 0x780
	s_cselect_b32 s50, 0, s50
	s_add_i32 s47, s47, 1
	s_xor_b32 s75, s75, 1
	s_waitcnt vmcnt(0) lgkmcnt(0)
	s_barrier
	s_cmpk_lg_i32 s47, 15
	s_cbranch_scc1 .Lp4_gloop
	v_mfma_f32_16x16x32_bf16 v[24:27], v[230:233], v[198:201], v[24:27]
	v_mfma_f32_16x16x32_bf16 v[20:23], v[234:237], v[198:201], v[20:23]
	v_mfma_f32_16x16x32_bf16 v[16:19], v[238:241], v[198:201], v[16:19]
	v_mfma_f32_16x16x32_bf16 v[12:15], v[242:245], v[198:201], v[12:15]
	v_mfma_f32_16x16x32_bf16 v[8:11], v[230:233], v[202:205], v[8:11]
	v_mfma_f32_16x16x32_bf16 v[4:7], v[234:237], v[202:205], v[4:7]
	v_mfma_f32_16x16x32_bf16 v[0:3], v[238:241], v[202:205], v[0:3]
	v_mfma_f32_16x16x32_bf16 v[56:59], v[242:245], v[202:205], v[56:59]
